# combo9 + GQA unit prologue de-serialisation (softmax reference load overlapped with the first K/V LDS-DMA and Q loads)
# baseline (speedup 1.0000x reference)
; __device__ __forceinline__ int opaque_tid() { int t; asm volatile("v_mov_b32 %0, %1" : "=v"(t) : "v"((int)threadIdx.x)); return t; }
; #define DMA_K(t, slot) glds16s(kvo, Kh + (long)TROW(t) * PITCH, (unsigned)__builtin_amdgcn_readfirstlane(kdst + (slot)))
; #define DMA_V(t, slot) glds16s(vvo, Vh + (long)TROW(t) * PITCH, (unsigned)__builtin_amdgcn_readfirstlane(vdst + (slot)))
;     const int tid = opaque_tid(), lane = tid & 63, r32 = lane & 31, hi = lane >> 5; const int wid = __builtin_amdgcn_readfirstlane(tid >> 6);
;     const bf16_t* Qw = Q + (long)(wid * QBLK) * PITCH;
;     const unsigned lds0 = (unsigned)(uintptr_t)shm;
;     float* wsf = (float*)(shm + LDS_WS) + wid * 64;
;     const unsigned kvo = (unsigned)((lane * PITCH + wid * 8) * 2);
;     const unsigned vvo = (unsigned)(((16 * (wid & 3) + (lane >> 2)) * PITCH + (wid >> 2) * 32 + (lane & 3) * 8) * 2);
;     const unsigned kdst = lds0 + LDS_K + wid * 1024, vdst = lds0 + LDS_V + wid * 1024;
;     ...
;     const char* Kbase = shm + LDS_K; bf16x8 kf[8];
;     const lds_cptr shm3 = (lds_cptr)shm; const lds_cptr kp0 = shm3 + LDS_K + hi * 1024 + r32 * 16; const lds_cptr vp0 = shm3 + LDS_V + ((lane >> 4) & 1) * 32 + (lane & 3) * 8 + (4 * hi + ((lane & 15) >> 2)) * 64;
;     DMA_K(0, 0); DMA_V(0, 0); DMA_K(1, SLOTB);
;     bf16x8 qr[4];
; #pragma unroll
;     for (int d0 = 0; d0 < 4; ++d0) qr[d0] = *reinterpret_cast<const bf16x8*>(&Qw[(long)r32 * PITCH + d0 * 16 + hi * 8]);
;     float mhat = (MODE == 0) ? bref : 0.f, l_reg = 0.f; f32x16 o[2]; o[0] = f32x16{}; o[1] = f32x16{}; f32x16 negm = f32x16{};
;     if (MODE == 0) { _Pragma("unroll") for (int r = 0; r < 16; ++r) negm[r] = -bref; }
; __global__ void __launch_bounds__(NTHREADS, 2) mega_fwd(Params P) {
;     ...
;                 if (idx < n_gqa) {
;                     const int qb = idx / 12, r12 = idx % 12, b = r12 / 6, h = r12 % 6; const size_t rb = (size_t)b * RPB;
;                     ap::unit<8, 0>(qkv + (rb + 256 * qb) * DIN + C_QC + 64 * h, qkv + rb * DIN + C_KC + 64 * (h / 3), qkv + rb * DIN + C_VC + 64 * (h / 3),
;                                    omix + (rb + 256 * qb) * DM + 640 + 64 * h, ssb + (rb + 256 * qb) * 4 + 2, 132, (char*)lds, 0, 0, tcos[4096 + l]);
.LBB0_874:
	s_andn2_b64 vcc, exec, s[0:1]
	s_cbranch_vccnz .LBB0_439
	s_mul_hi_i32 s0, s48, 0x2aaaaaab
	s_lshr_b32 s1, s0, 31
	s_ashr_i32 s3, s0, 1
	s_add_i32 s3, s3, s1
	s_mul_i32 s0, s3, 12
	s_sub_i32 s0, s48, s0
	s_mul_i32 s1, s0, 43
	s_bfe_u32 s2, s1, 0x1000f
	s_bfe_u32 s1, s1, 0x80008
	s_add_i32 s1, s1, s2
	s_sext_i32_i8 s18, s1
	s_mul_i32 s1, s1, 6
	s_mul_i32 s9, s18, 0x2100
	s_lshl_b32 s4, s3, 8
	s_sub_i32 s8, s0, s1
	s_ashr_i32 s5, s9, 31
	s_ashr_i32 s6, s4, 31
	s_add_u32 s4, s9, s4
	s_addc_u32 s5, s5, s6
	s_mul_i32 s6, s5, 0x1200
	s_mul_hi_u32 s7, s4, 0x1200
	s_mov_b64 s[0:1], s[76:77]
	s_add_i32 s7, s7, s6
	s_mul_i32 s6, s4, 0x1200
	s_sext_i32_i8 s2, s8
	s_add_u32 s10, s0, s6
	s_addc_u32 s11, s1, s7
	s_lshl_b32 s0, s2, 6
	s_ashr_i32 s1, s0, 31
	s_lshl_b64 s[6:7], s[0:1], 1
	s_add_u32 s26, s10, s6
	s_addc_u32 s27, s11, s7
	s_mov_b64 s[0:1], s[76:77]
	s_mul_i32 s10, s18, 0x2520000
	s_mul_hi_i32 s9, s9, 0x1200
	s_add_u32 s2, s0, s10
	s_addc_u32 s22, s1, s9
	s_bfe_i32 s0, s8, 0x80000
	s_mulk_i32 s0, 0x56
	s_bfe_u32 s1, s0, 0x1000f
	s_bfe_u32 s0, s0, 0x80008
	s_add_i32 s0, s0, s1
	s_sext_i32_i8 s0, s0
	s_lshl_b32 s0, s0, 6
	s_ashr_i32 s1, s0, 31
	s_lshl_b64 s[16:17], s[0:1], 1
	s_add_u32 s30, s2, s16
	s_addc_u32 s34, s22, s17
	s_add_u32 s14, s30, 0xe400300
	s_addc_u32 s15, s34, 0
	s_mov_b64 s[0:1], s[76:77]
	s_add_u32 s23, s0, s10
	s_addc_u32 s24, s1, s9
	s_add_u32 s35, s23, s16
	s_addc_u32 s36, s24, s17
	v_readlane_b32 s20, v252, 9
	s_add_u32 s12, s35, 0xe401100
	s_mov_b64 s[10:11], s[76:77]
	s_mov_b64 s[8:9], s[76:77]
	s_mov_b64 s[0:1], s[76:77]
	v_readlane_b32 s21, v252, 10
	s_addc_u32 s13, s36, 0
	s_lshl_b64 s[20:21], s[20:21], 2
	s_add_u32 s0, s0, s20
	s_addc_u32 s1, s1, s21
	v_mov_b32_e32 v0, s0
	s_mov_b32 s0, 0x184000
	v_mov_b32_e32 v3, s1
	v_add_co_u32_e32 v2, vcc, s0, v0
	v_mov_b32_e32 v194, 0
	s_nop 0
	v_addc_co_u32_e32 v3, vcc, 0, v3, vcc
	flat_load_dword v50, v[2:3]
	v_mov_b32 v14, v214
	s_nop 1
	v_readfirstlane_b32 s25, v14
	s_ashr_i32 s19, s25, 6
	s_cmp_ge_u32 s19, 4
	s_cbranch_scc0 .Lgqa_prio_skip
	s_setprio 1
; #define WAIT_BAR(N) asm volatile("s_waitcnt vmcnt(" #N ") lgkmcnt(0)\n\ts_barrier" ::: "memory")
; #define DMA_K(t, slot) glds16s(kvo, Kh + (long)TROW(t) * PITCH, (unsigned)__builtin_amdgcn_readfirstlane(kdst + (slot)))
; #define DMA_V(t, slot) glds16s(vvo, Vh + (long)TROW(t) * PITCH, (unsigned)__builtin_amdgcn_readfirstlane(vdst + (slot)))
; #define ROT() do { sl_prev = sl_cur; sl_cur = sl_next; sl_next = (sl_next == (NSLOT - 1) * SLOTB) ? 0 : sl_next + SLOTB; } while (0)
;     ...
;     const unsigned kvo = (unsigned)((lane * PITCH + wid * 8) * 2);
;     const unsigned vvo = (unsigned)(((16 * (wid & 3) + (lane >> 2)) * PITCH + (wid >> 2) * 32 + (lane & 3) * 8) * 2);
;     const unsigned kdst = lds0 + LDS_K + wid * 1024, vdst = lds0 + LDS_V + wid * 1024;
;     ...
;     const char* Kbase = shm + LDS_K; bf16x8 kf[8];
;     const lds_cptr shm3 = (lds_cptr)shm; const lds_cptr kp0 = shm3 + LDS_K + hi * 1024 + r32 * 16; const lds_cptr vp0 = shm3 + LDS_V + ((lane >> 4) & 1) * 32 + (lane & 3) * 8 + (4 * hi + ((lane & 15) >> 2)) * 64;
;     DMA_K(0, 0); DMA_V(0, 0); DMA_K(1, SLOTB);
;     bf16x8 qr[4];
; #pragma unroll
;     for (int d0 = 0; d0 < 4; ++d0) qr[d0] = *reinterpret_cast<const bf16x8*>(&Qw[(long)r32 * PITCH + d0 * 16 + hi * 8]);
;     float mhat = (MODE == 0) ? bref : 0.f, l_reg = 0.f; f32x16 o[2]; o[0] = f32x16{}; o[1] = f32x16{}; f32x16 negm = f32x16{};
;     if (MODE == 0) { _Pragma("unroll") for (int r = 0; r < 16; ++r) negm[r] = -bref; }
;     if (MODE != 1) asm volatile("" : "+v"(negm));
;     int na_gr = 0, na_rs = 0, na_qc = 0, na_cs = 0;
;     if (MODE == 1) { na_gr = r0 + (wid >> 1); na_rs = min(max(na_gr - 4, 0), 120); na_qc = 32 * (wid & 1) + r32; na_cs = min(max(na_qc - 8, 0), 48); }
;     ...
;     bool resc = false;
;     ...
;     f32x16 pA0, pA1, pB0, pB1;
;     int sl_prev = 0, sl_cur = 0, sl_next = SLOTB;
;     ...
;     DMA_K(2, 2 * SLOTB);
;     WAIT_BAR(3);
;     qkt(pA0, pA1, Kbase, qr, negm, r32, hi); asm volatile("s_nop 15\n\ts_nop 7" : "+v"(pA0), "+v"(pA1));
;     START(pA0, pA1);
;     _Pragma("unroll") for (int r = 0; r < 16; ++r) pA1[r] = __builtin_amdgcn_exp2f(pA1[r]);
;     WAIT_BAR(0);
;     DMA_K(3, 0); DMA_V(1, SLOTB);
;     ROT();
;     kload8(kf, kp0 + sl_cur);
;     WAIT_BAR(2);
;     s16x4 vlo[8], vhi[8]; u32x4 pw0, pw1, pw2, pw3;
.Lgqa_prio_skip:
	s_lshl_b32 s0, s19, 5
	s_ashr_i32 s1, s0, 31
	s_mul_i32 s20, s19, 0x24000
	s_mul_hi_i32 s21, s0, 0x1200
	s_add_u32 s28, s26, s20
	s_addc_u32 s29, s27, s21
	s_lshl_b32 s20, s19, 4
	v_and_b32_e32 v15, 63, v14
	v_mov_b32_e32 v0, s20
	v_mad_u32_u24 v193, v15, s80, v0
	v_bfe_u32 v0, v14, 2, 4
	v_and_or_b32 v0, s20, 48, v0
	s_ashr_i32 s20, s25, 3
	s_and_b32 s20, s20, 0x7fffffe0
	v_mov_b32_e32 v2, s20
	v_mad_u32_u24 v0, v0, s81, v2
	v_lshlrev_b32_e32 v2, 3, v14
	v_and_b32_e32 v187, 24, v2
	v_and_b32_e32 v17, 31, v14
	v_or_b32_e32 v0, v0, v187
	s_lshl_b32 s21, s19, 10
	v_lshlrev_b32_e32 v192, 1, v0
	s_cmp_lg_u32 0, -1
	v_mul_u32_u24_e32 v0, 0x900, v17
	v_bfe_u32 v186, v14, 5, 1
	s_cselect_b32 s20, 0, 0
	v_lshlrev_b32_e32 v0, 1, v0
	s_add_i32 s26, s21, s20
	v_lshl_or_b32 v0, v186, 4, v0
	s_add_i32 s20, s26, 0x6000
	s_mov_b32 s27, m0
	s_mov_b32 m0, s26
	s_nop 0
	global_load_lds_dwordx4 v193, s[14:15]
	s_mov_b32 m0, s27
	v_lshl_add_u64 v[2:3], s[28:29], 0, v[0:1]
	s_mov_b32 s27, m0
	s_mov_b32 m0, s20
	s_nop 0
	global_load_lds_dwordx4 v192, s[12:13]
	s_mov_b32 m0, s27
	s_add_u32 s38, s30, 0xe448300
	v_add_co_u32_e32 v4, vcc, s82, v2
	s_addc_u32 s39, s34, 0
	s_add_i32 s27, s26, 0x2000
	s_mov_b32 s31, m0
	s_mov_b32 m0, s27
	s_nop 0
	global_load_lds_dwordx4 v193, s[38:39]
	s_mov_b32 m0, s31
	v_addc_co_u32_e32 v5, vcc, 0, v3, vcc
	flat_load_dwordx4 v[162:165], v[4:5]
	s_mov_b64 s[28:29], 0xe400000
	v_lshl_add_u64 v[2:3], v[2:3], 0, s[28:29]
	flat_load_dwordx4 v[158:161], v[2:3] offset:32
	flat_load_dwordx4 v[154:157], v[2:3] offset:64
	flat_load_dwordx4 v[150:153], v[2:3] offset:96
	s_add_u32 s28, s30, 0xe490300
	v_lshlrev_b32_e32 v0, 10, v186
	v_lshlrev_b32_e32 v4, 4, v17
	s_addc_u32 s29, s34, 0
	s_add_i32 s27, s26, 0x4000
	s_mov_b32 s31, m0
	s_mov_b32 m0, s27
	s_nop 0
	global_load_lds_dwordx4 v193, s[28:29]
	s_mov_b32 m0, s31
	v_add3_u32 v191, 0, v0, v4
	s_waitcnt vmcnt(3) lgkmcnt(0)
	s_barrier
	ds_read_b128 v[2:5], v191
	ds_read_b128 v[6:9], v191 offset:512
	s_waitcnt vmcnt(0) lgkmcnt(0)
	v_xor_b32_e32 v50, 0x80000000, v50
	v_mov_b32_e32 v51, v50
	v_mov_b32_e32 v52, v50
	v_mov_b32_e32 v53, v50
	v_mov_b32_e32 v54, v50
	v_mov_b32_e32 v55, v50
	v_mov_b32_e32 v56, v50
	v_mov_b32_e32 v57, v50
	v_mov_b32_e32 v58, v50
	v_mov_b32_e32 v59, v50
	v_mov_b32_e32 v60, v50
	v_mov_b32_e32 v61, v50
	v_mov_b32_e32 v62, v50
	v_mov_b32_e32 v63, v50
	v_mov_b32_e32 v64, v50
	v_mov_b32_e32 v65, v50
	s_nop 1
	v_mfma_f32_32x32x16_bf16 v[34:49], v[2:5], v[162:165], v[50:65]
	s_add_u32 s38, s30, 0xe4d8300
	s_addc_u32 s39, s34, 0
	s_add_u32 s34, s35, 0xe449100
	s_addc_u32 s35, s36, 0
	v_lshlrev_b32_e32 v0, 1, v14
	v_and_b32_e32 v188, 32, v0
	v_lshlrev_b32_e32 v0, 8, v186
	v_mfma_f32_32x32x16_bf16 v[18:33], v[6:9], v[162:165], v[50:65]
	ds_read_b128 v[2:5], v191 offset:2048
	ds_read_b128 v[6:9], v191 offset:2560
	s_mov_b32 s31, 0
	s_mov_b32 s27, -1
	s_movk_i32 s29, 0x2000
	s_movk_i32 s28, 0x4000
	s_waitcnt lgkmcnt(1)
	v_mfma_f32_32x32x16_bf16 v[34:49], v[2:5], v[158:161], v[34:49]
	s_waitcnt lgkmcnt(0)
	v_mfma_f32_32x32x16_bf16 v[18:33], v[6:9], v[158:161], v[18:33]
	ds_read_b128 v[2:5], v191 offset:4096
	ds_read_b128 v[6:9], v191 offset:4608
	s_waitcnt lgkmcnt(1)
	v_mfma_f32_32x32x16_bf16 v[34:49], v[2:5], v[154:157], v[34:49]
	s_waitcnt lgkmcnt(0)
	v_mfma_f32_32x32x16_bf16 v[18:33], v[6:9], v[154:157], v[18:33]
	ds_read_b128 v[2:5], v191 offset:6144
	ds_read_b128 v[6:9], v191 offset:6656
	s_waitcnt lgkmcnt(1)
	v_mfma_f32_32x32x16_bf16 v[34:49], v[2:5], v[150:153], v[34:49]
	v_lshlrev_b32_e32 v3, 4, v14
	v_add_u32_e32 v2, 0, v188
	v_and_or_b32 v189, v3, s83, v0
	v_add3_u32 v190, v2, v187, v189
	s_waitcnt lgkmcnt(0)
	v_mfma_f32_32x32x16_bf16 v[18:33], v[6:9], v[150:153], v[18:33]
	s_nop 15
	s_nop 7
	s_waitcnt vmcnt(0) lgkmcnt(0)
	s_barrier
	s_mov_b32 s30, m0
	s_mov_b32 m0, s26
	s_nop 0
	global_load_lds_dwordx4 v193, s[38:39]
	s_mov_b32 m0, s30
	s_add_i32 s30, s26, 0x8000
	s_mov_b32 s36, m0
	s_mov_b32 m0, s30
	s_nop 0
	global_load_lds_dwordx4 v192, s[34:35]
	s_mov_b32 m0, s36
	ds_read_b128 v[98:101], v191 offset:8192
	ds_read_b128 v[170:173], v191 offset:8704
	ds_read_b128 v[174:177], v191 offset:10240
	ds_read_b128 v[166:169], v191 offset:10752
	ds_read_b128 v[142:145], v191 offset:12288
	ds_read_b128 v[138:141], v191 offset:12800
	ds_read_b128 v[134:137], v191 offset:14336
	ds_read_b128 v[130:133], v191 offset:14848
	v_exp_f32_e32 v82, v34
	v_exp_f32_e32 v83, v35
	v_exp_f32_e32 v84, v36
	v_exp_f32_e32 v85, v37
	v_exp_f32_e32 v86, v38
	v_exp_f32_e32 v87, v39
	v_exp_f32_e32 v88, v40
	v_exp_f32_e32 v89, v41
	v_exp_f32_e32 v90, v42
	v_exp_f32_e32 v91, v43
	v_exp_f32_e32 v92, v44
	v_exp_f32_e32 v93, v45
	v_exp_f32_e32 v94, v46
	v_exp_f32_e32 v95, v47
	v_exp_f32_e32 v96, v48
	v_exp_f32_e32 v97, v49
	v_exp_f32_e32 v66, v18
	v_exp_f32_e32 v67, v19
	v_exp_f32_e32 v68, v20
	v_exp_f32_e32 v69, v21
	v_exp_f32_e32 v70, v22
	v_exp_f32_e32 v71, v23
	v_exp_f32_e32 v72, v24
	v_exp_f32_e32 v73, v25
	v_exp_f32_e32 v74, v26
	v_exp_f32_e32 v75, v27
	v_exp_f32_e32 v76, v28
	v_exp_f32_e32 v77, v29
	v_exp_f32_e32 v78, v30
	v_exp_f32_e32 v79, v31
	v_exp_f32_e32 v80, v32
	v_exp_f32_e32 v81, v33
	s_waitcnt vmcnt(2) lgkmcnt(0)
	s_barrier
	v_mov_b32_e32 v18, 0
	v_mov_b32_e32 v19, v194
	v_mov_b32_e32 v20, v194
	v_mov_b32_e32 v21, v194
	v_mov_b32_e32 v22, v194
	v_mov_b32_e32 v23, v194
	v_mov_b32_e32 v24, v194
	v_mov_b32_e32 v25, v194
	v_mov_b32_e32 v26, v194
	v_mov_b32_e32 v27, v194
	v_mov_b32_e32 v28, v194
	v_mov_b32_e32 v29, v194
	v_mov_b32_e32 v30, v194
	v_mov_b32_e32 v31, v194
	v_mov_b32_e32 v32, v194
	v_mov_b32_e32 v33, v194
	v_mov_b32_e32 v34, 0
	v_mov_b32_e32 v35, v194
	v_mov_b32_e32 v36, v194
	v_mov_b32_e32 v37, v194
	v_mov_b32_e32 v38, v194
	v_mov_b32_e32 v39, v194
	v_mov_b32_e32 v40, v194
	v_mov_b32_e32 v41, v194
	v_mov_b32_e32 v42, v194
	v_mov_b32_e32 v43, v194
	v_mov_b32_e32 v44, v194
	v_mov_b32_e32 v45, v194
	v_mov_b32_e32 v46, v194
	v_mov_b32_e32 v47, v194
	v_mov_b32_e32 v48, v194
	v_mov_b32_e32 v49, v194
